# P5 tile epilogue: first row-group's residual loads issued one double batch ahead (no load round trip / store drain at each batch start)
# baseline (speedup 1.0000x reference)
.LBB0_620:
	v_readlane_b32 s80, v242, 21
	v_lshlrev_b32_e32 v114, 3, v158
	v_or_b32_e32 v115, s47, v148
	v_readlane_b32 s81, v242, 22
	v_add_u32_e32 v150, s35, v115
	v_lshl_or_b32 v114, s12, 5, v114
	v_readlane_b32 s82, v242, 23
	v_readlane_b32 s83, v242, 24
	s_mov_b64 s[36:37], s[80:81]
	v_or_b32_e32 v148, s34, v114
	v_add_u32_e32 v114, 0xffffc000, v150
	v_ashrrev_i32_e32 v151, 31, v150
	v_cmp_gt_i32_e32 vcc, s45, v150
	s_mov_b64 s[38:39], s[82:83]
	v_mov_b32_e32 v118, s39
	v_cndmask_b32_e32 v115, 0, v151, vcc
	v_cndmask_b32_e32 v114, v114, v150, vcc
	v_mov_b32_e32 v119, s37
	v_mov_b32_e32 v120, s38
	v_mov_b32_e32 v121, s36
	v_ashrrev_i32_e32 v149, 31, v148
	v_cndmask_b32_e32 v117, v118, v119, vcc
	v_cndmask_b32_e32 v116, v120, v121, vcc
	v_lshlrev_b64 v[114:115], 12, v[114:115]
	v_lshl_add_u64 v[114:115], v[116:117], 0, v[114:115]
	v_lshlrev_b64 v[152:153], 2, v[148:149]
	v_lshl_add_u64 v[114:115], v[114:115], 0, v[152:153]
	v_mov_b32_e32 v176, v114
	v_mov_b32_e32 v177, v115
	global_load_dwordx4 v[160:163], v[114:115], off
	global_load_dwordx4 v[164:167], v[114:115], off offset:16
	global_load_dwordx4 v[168:171], v[114:115], off offset:512
	global_load_dwordx4 v[172:175], v[114:115], off offset:528
	v_or_b32_e32 v154, 16, v150
	v_add_u32_e32 v114, 0xffffc010, v150
	v_ashrrev_i32_e32 v155, 31, v154
	v_cmp_gt_i32_e32 vcc, s45, v154
	v_readlane_b32 s84, v242, 25
	v_readlane_b32 s85, v242, 26
	v_cndmask_b32_e32 v115, 0, v155, vcc
	v_cndmask_b32_e32 v114, v114, v154, vcc
	v_cndmask_b32_e32 v117, v118, v119, vcc
	v_cndmask_b32_e32 v116, v120, v121, vcc
	v_lshlrev_b64 v[114:115], 12, v[114:115]
	v_lshl_add_u64 v[114:115], v[116:117], 0, v[114:115]
	v_lshl_add_u64 v[118:119], v[114:115], 0, v[152:153]
	global_load_dwordx4 v[130:133], v[118:119], off offset:16
	global_load_dwordx4 v[138:141], v[118:119], off
	global_load_dwordx4 v[114:117], v[118:119], off offset:528
	s_nop 0
	global_load_dwordx4 v[118:121], v[118:119], off offset:512
	s_mov_b64 s[96:97], 0x20000
	v_lshl_add_u64 v[178:179], v[176:177], 0, s[96:97]
	global_load_dwordx4 v[186:189], v[178:179], off
	global_load_dwordx4 v[190:193], v[178:179], off offset:16
	global_load_dwordx4 v[194:197], v[178:179], off offset:512
	global_load_dwordx4 v[198:201], v[178:179], off offset:528
	v_cmp_eq_u32_e32 vcc, 0, v158
	v_readlane_b32 s86, v242, 27
	v_readlane_b32 s87, v242, 28
	v_readlane_b32 s88, v242, 29
	v_readlane_b32 s89, v242, 30
	v_readlane_b32 s90, v242, 31
	v_readlane_b32 s91, v242, 32
	v_readlane_b32 s92, v242, 33
	v_readlane_b32 s93, v242, 34
	v_readlane_b32 s94, v242, 35
	v_readlane_b32 s95, v242, 36
	s_waitcnt vmcnt(4)
	v_pk_add_f32 v[144:145], v[144:145], v[162:163]
	v_pk_add_f32 v[142:143], v[142:143], v[160:161]
	v_pk_add_f32 v[136:137], v[136:137], v[166:167]
	v_pk_add_f32 v[134:135], v[134:135], v[164:165]
	v_pk_add_f32 v[158:159], v[128:129], v[170:171]
	v_pk_add_f32 v[160:161], v[126:127], v[168:169]
	v_pk_add_f32 v[124:125], v[124:125], v[174:175]
	v_pk_add_f32 v[122:123], v[122:123], v[172:173]
	v_cvt_pk_bf16_f32 v126, v142, v143
	v_cvt_pk_bf16_f32 v127, v144, v145
	v_cvt_pk_bf16_f32 v128, v134, v135
	v_cvt_pk_bf16_f32 v129, v136, v137
	v_cvt_pk_bf16_f32 v134, v160, v161
	v_cvt_pk_bf16_f32 v135, v158, v159
	s_nop 0
	v_cvt_pk_bf16_f32 v136, v122, v123
	v_cvt_pk_bf16_f32 v137, v124, v125
	v_and_b32_e32 v123, 0xffff0000, v126
	v_and_b32_e32 v125, 0xffff0000, v127
	v_and_b32_e32 v143, 0xffff0000, v128
	v_and_b32_e32 v145, 0xffff0000, v129
	v_and_b32_e32 v158, 0xffff0000, v134
	v_and_b32_e32 v160, 0xffff0000, v135
	v_and_b32_e32 v162, 0xffff0000, v136
	v_and_b32_e32 v164, 0xffff0000, v137
	v_lshlrev_b32_e32 v122, 16, v126
	v_lshlrev_b32_e32 v124, 16, v127
	v_lshlrev_b32_e32 v142, 16, v128
	v_lshlrev_b32_e32 v144, 16, v129
	v_lshlrev_b32_e32 v146, 16, v134
	v_lshlrev_b32_e32 v159, 16, v135
	v_lshlrev_b32_e32 v161, 16, v136
	v_lshlrev_b32_e32 v163, 16, v137
	v_mul_f32_e32 v123, v123, v123
	v_mul_f32_e32 v125, v125, v125
	v_mul_f32_e32 v143, v143, v143
	v_mul_f32_e32 v145, v145, v145
	v_mul_f32_e32 v158, v158, v158
	v_mul_f32_e32 v160, v160, v160
	v_mul_f32_e32 v162, v162, v162
	v_mul_f32_e32 v164, v164, v164
	v_fmac_f32_e32 v123, v122, v122
	v_fmac_f32_e32 v125, v124, v124
	v_fmac_f32_e32 v143, v142, v142
	v_fmac_f32_e32 v145, v144, v144
	v_fmac_f32_e32 v158, v146, v146
	v_fmac_f32_e32 v160, v159, v159
	v_fmac_f32_e32 v162, v161, v161
	v_fmac_f32_e32 v164, v163, v163
	v_add_f32_e32 v122, v123, v125
	v_add_f32_e32 v123, v143, v145
	v_add_f32_e32 v124, v158, v160
	v_add_f32_e32 v125, v162, v164
	v_add_f32_e32 v122, v122, v123
	v_add_f32_e32 v123, v124, v125
	v_and_b32_e32 v124, 64, v156
	v_add_f32_e32 v123, v122, v123
	v_xor_b32_e32 v122, 16, v156
	v_add_u32_e32 v125, 64, v124
	v_cmp_lt_i32_e64 s[4:5], v122, v125
	v_lshlrev_b64 v[142:143], 11, v[150:151]
	v_lshl_add_u64 v[142:143], s[2:3], 0, v[142:143]
	v_cndmask_b32_e64 v122, v156, v122, s[4:5]
	v_lshlrev_b32_e32 v122, 2, v122
	ds_bpermute_b32 v124, v122, v123
	s_lshr_b32 s4, s34, 6
	s_and_b32 s4, s4, 12
	s_or_b32 s34, s4, s12
	v_lshl_add_u64 v[142:143], v[148:149], 1, v[142:143]
	s_waitcnt lgkmcnt(0)
	v_add_f32_e32 v124, v123, v124
	v_xor_b32_e32 v123, 32, v156
	v_cmp_lt_i32_e64 s[4:5], v123, v125
	global_store_dwordx4 v[142:143], v[126:129], off
	global_store_dwordx4 v[142:143], v[134:137], off offset:256
	v_cndmask_b32_e64 v123, v156, v123, s[4:5]
	v_lshlrev_b32_e32 v123, 2, v123
	ds_bpermute_b32 v125, v123, v124
	s_and_saveexec_b64 s[4:5], vcc
	s_cbranch_execz .LBB0_622
	v_lshlrev_b64 v[126:127], 6, v[150:151]
	v_lshl_add_u64 v[126:127], s[8:9], 0, v[126:127]
	s_lshl_b32 s12, s34, 2
	v_lshl_add_u64 v[126:127], v[126:127], 0, s[12:13]
	s_waitcnt lgkmcnt(0)
	v_add_f32_e32 v124, v124, v125
	global_store_dword v[126:127], v124, off

.LBB0_624:
	s_or_b64 exec, exec, s[4:5]
	v_readlane_b32 s80, v242, 21
	v_readlane_b32 s81, v242, 22
	v_or_b32_e32 v116, 32, v150
	v_readlane_b32 s82, v242, 23
	v_readlane_b32 s83, v242, 24
	s_mov_b64 s[36:37], s[80:81]
	v_add_u32_e32 v98, 0xffffc020, v150
	v_ashrrev_i32_e32 v117, 31, v116
	v_cmp_gt_i32_e64 s[4:5], s45, v116
	s_mov_b64 s[38:39], s[82:83]
	v_mov_b32_e32 v102, s39
	s_waitcnt lgkmcnt(0)
	v_cndmask_b32_e64 v99, 0, v117, s[4:5]
	v_cndmask_b32_e64 v98, v98, v116, s[4:5]
	v_mov_b32_e32 v103, s37
	v_mov_b32_e32 v104, s38
	v_mov_b32_e32 v105, s36
	v_cndmask_b32_e64 v101, v102, v103, s[4:5]
	v_cndmask_b32_e64 v100, v104, v105, s[4:5]
	v_lshlrev_b64 v[98:99], 12, v[98:99]
	v_lshl_add_u64 v[98:99], v[100:101], 0, v[98:99]
	v_lshl_add_u64 v[98:99], v[98:99], 0, v[152:153]
	v_or_b32_e32 v114, 48, v150
	v_add_u32_e32 v98, 0xffffc030, v150
	v_ashrrev_i32_e32 v115, 31, v114
	v_cmp_gt_i32_e64 s[4:5], s45, v114
	v_readlane_b32 s84, v242, 25
	v_readlane_b32 s85, v242, 26
	v_cndmask_b32_e64 v99, 0, v115, s[4:5]
	v_cndmask_b32_e64 v98, v98, v114, s[4:5]
	v_cndmask_b32_e64 v101, v102, v103, s[4:5]
	v_cndmask_b32_e64 v100, v104, v105, s[4:5]
	v_lshlrev_b64 v[98:99], 12, v[98:99]
	v_lshl_add_u64 v[98:99], v[100:101], 0, v[98:99]
	v_lshl_add_u64 v[102:103], v[98:99], 0, v[152:153]
	global_load_dwordx4 v[106:109], v[102:103], off offset:16
	global_load_dwordx4 v[110:113], v[102:103], off
	global_load_dwordx4 v[98:101], v[102:103], off offset:528
	s_nop 0
	global_load_dwordx4 v[102:105], v[102:103], off offset:512
	s_mov_b64 s[96:97], 0x80000
	v_lshl_add_u64 v[178:179], v[176:177], 0, s[96:97]
	global_load_dwordx4 v[202:205], v[178:179], off
	global_load_dwordx4 v[206:209], v[178:179], off offset:16
	global_load_dwordx4 v[210:213], v[178:179], off offset:512
	global_load_dwordx4 v[214:217], v[178:179], off offset:528
	v_readlane_b32 s86, v242, 27
	v_readlane_b32 s87, v242, 28
	v_readlane_b32 s88, v242, 29
	v_readlane_b32 s89, v242, 30
	v_readlane_b32 s90, v242, 31
	v_readlane_b32 s91, v242, 32
	v_readlane_b32 s92, v242, 33
	v_readlane_b32 s93, v242, 34
	v_readlane_b32 s94, v242, 35
	v_readlane_b32 s95, v242, 36
	s_waitcnt vmcnt(12)
	v_pk_add_f32 v[96:97], v[96:97], v[188:189]
	v_pk_add_f32 v[94:95], v[94:95], v[186:187]
	v_pk_add_f32 v[92:93], v[92:93], v[192:193]
	v_pk_add_f32 v[90:91], v[90:91], v[190:191]
	v_pk_add_f32 v[118:119], v[88:89], v[196:197]
	v_pk_add_f32 v[88:89], v[86:87], v[194:195]
	v_pk_add_f32 v[120:121], v[84:85], v[200:201]
	v_pk_add_f32 v[82:83], v[82:83], v[198:199]
	v_cvt_pk_bf16_f32 v84, v94, v95
	v_cvt_pk_bf16_f32 v85, v96, v97
	v_cvt_pk_bf16_f32 v86, v90, v91
	v_cvt_pk_bf16_f32 v87, v92, v93
	v_cvt_pk_bf16_f32 v88, v88, v89
	v_cvt_pk_bf16_f32 v89, v118, v119
	s_nop 0
	v_cvt_pk_bf16_f32 v90, v82, v83
	v_cvt_pk_bf16_f32 v91, v120, v121
	v_and_b32_e32 v83, 0xffff0000, v84
	v_and_b32_e32 v93, 0xffff0000, v85
	v_and_b32_e32 v95, 0xffff0000, v86
	v_and_b32_e32 v97, 0xffff0000, v87
	v_and_b32_e32 v119, 0xffff0000, v88
	v_and_b32_e32 v121, 0xffff0000, v89
	v_and_b32_e32 v125, 0xffff0000, v90
	v_and_b32_e32 v127, 0xffff0000, v91
	v_lshlrev_b32_e32 v82, 16, v84
	v_lshlrev_b32_e32 v92, 16, v85
	v_lshlrev_b32_e32 v94, 16, v86
	v_lshlrev_b32_e32 v96, 16, v87
	v_lshlrev_b32_e32 v118, 16, v88
	v_lshlrev_b32_e32 v120, 16, v89
	v_lshlrev_b32_e32 v124, 16, v90
	v_lshlrev_b32_e32 v126, 16, v91
	v_mul_f32_e32 v83, v83, v83
	v_mul_f32_e32 v93, v93, v93
	v_mul_f32_e32 v95, v95, v95
	v_mul_f32_e32 v97, v97, v97
	v_mul_f32_e32 v119, v119, v119
	v_mul_f32_e32 v121, v121, v121
	v_mul_f32_e32 v125, v125, v125
	v_mul_f32_e32 v127, v127, v127
	v_fmac_f32_e32 v83, v82, v82
	v_fmac_f32_e32 v93, v92, v92
	v_fmac_f32_e32 v95, v94, v94
	v_fmac_f32_e32 v97, v96, v96
	v_fmac_f32_e32 v119, v118, v118
	v_fmac_f32_e32 v121, v120, v120
	v_fmac_f32_e32 v125, v124, v124
	v_fmac_f32_e32 v127, v126, v126
	v_add_f32_e32 v82, v83, v93
	v_add_f32_e32 v83, v95, v97
	v_add_f32_e32 v92, v119, v121
	v_add_f32_e32 v93, v125, v127
	v_add_f32_e32 v82, v82, v83
	v_add_f32_e32 v83, v92, v93
	v_add_f32_e32 v82, v82, v83
	ds_bpermute_b32 v83, v122, v82
	v_lshlrev_b64 v[92:93], 11, v[116:117]
	v_lshl_add_u64 v[92:93], s[2:3], 0, v[92:93]
	v_lshl_add_u64 v[92:93], v[148:149], 1, v[92:93]
	s_waitcnt vmcnt(4)
	global_store_dwordx4 v[92:93], v[84:87], off
	global_store_dwordx4 v[92:93], v[88:91], off offset:256
	s_waitcnt lgkmcnt(0)
	v_add_f32_e32 v82, v82, v83
	ds_bpermute_b32 v83, v123, v82
	s_and_saveexec_b64 s[4:5], vcc
	s_cbranch_execz .LBB0_626
	v_lshlrev_b64 v[84:85], 6, v[116:117]
	v_lshl_add_u64 v[84:85], s[8:9], 0, v[84:85]
	s_lshl_b32 s12, s34, 2
	v_lshl_add_u64 v[84:85], v[84:85], 0, s[12:13]
	s_waitcnt lgkmcnt(0)
	v_add_f32_e32 v82, v82, v83
	global_store_dword v[84:85], v82, off

.LBB0_628:
	s_or_b64 exec, exec, s[4:5]
	v_readlane_b32 s80, v242, 21
	v_readlane_b32 s81, v242, 22
	v_add_u32_e32 v84, 0x80, v150
	v_readlane_b32 s82, v242, 23
	v_readlane_b32 s83, v242, 24
	s_mov_b64 s[36:37], s[80:81]
	v_add_u32_e32 v66, 0xffffc080, v150
	v_ashrrev_i32_e32 v85, 31, v84
	v_cmp_gt_i32_e64 s[4:5], s45, v84
	s_mov_b64 s[38:39], s[82:83]
	v_mov_b32_e32 v70, s39
	s_waitcnt lgkmcnt(0)
	v_cndmask_b32_e64 v67, 0, v85, s[4:5]
	v_cndmask_b32_e64 v66, v66, v84, s[4:5]
	v_mov_b32_e32 v71, s37
	v_mov_b32_e32 v72, s38
	v_mov_b32_e32 v73, s36
	v_cndmask_b32_e64 v69, v70, v71, s[4:5]
	v_cndmask_b32_e64 v68, v72, v73, s[4:5]
	v_lshlrev_b64 v[66:67], 12, v[66:67]
	v_lshl_add_u64 v[66:67], v[68:69], 0, v[66:67]
	v_lshl_add_u64 v[66:67], v[66:67], 0, v[152:153]
	v_add_u32_e32 v82, 0x90, v150
	v_add_u32_e32 v66, 0xffffc090, v150
	v_ashrrev_i32_e32 v83, 31, v82
	v_cmp_gt_i32_e64 s[4:5], s45, v82
	v_readlane_b32 s84, v242, 25
	v_readlane_b32 s85, v242, 26
	v_cndmask_b32_e64 v67, 0, v83, s[4:5]
	v_cndmask_b32_e64 v66, v66, v82, s[4:5]
	v_cndmask_b32_e64 v69, v70, v71, s[4:5]
	v_cndmask_b32_e64 v68, v72, v73, s[4:5]
	v_lshlrev_b64 v[66:67], 12, v[66:67]
	v_lshl_add_u64 v[66:67], v[68:69], 0, v[66:67]
	v_lshl_add_u64 v[70:71], v[66:67], 0, v[152:153]
	global_load_dwordx4 v[74:77], v[70:71], off offset:16
	global_load_dwordx4 v[78:81], v[70:71], off
	global_load_dwordx4 v[66:69], v[70:71], off offset:528
	s_nop 0
	global_load_dwordx4 v[70:73], v[70:71], off offset:512
	s_mov_b64 s[96:97], 0xa0000
	v_lshl_add_u64 v[178:179], v[176:177], 0, s[96:97]
	global_load_dwordx4 v[186:189], v[178:179], off
	global_load_dwordx4 v[190:193], v[178:179], off offset:16
	global_load_dwordx4 v[194:197], v[178:179], off offset:512
	global_load_dwordx4 v[198:201], v[178:179], off offset:528
	v_readlane_b32 s86, v242, 27
	v_readlane_b32 s87, v242, 28
	v_readlane_b32 s88, v242, 29
	v_readlane_b32 s89, v242, 30
	v_readlane_b32 s90, v242, 31
	v_readlane_b32 s91, v242, 32
	v_readlane_b32 s92, v242, 33
	v_readlane_b32 s93, v242, 34
	v_readlane_b32 s94, v242, 35
	v_readlane_b32 s95, v242, 36
	s_waitcnt vmcnt(12)
	v_pk_add_f32 v[64:65], v[64:65], v[204:205]
	v_pk_add_f32 v[62:63], v[62:63], v[202:203]
	v_pk_add_f32 v[60:61], v[60:61], v[208:209]
	v_pk_add_f32 v[58:59], v[58:59], v[206:207]
	v_pk_add_f32 v[86:87], v[56:57], v[212:213]
	v_pk_add_f32 v[56:57], v[54:55], v[210:211]
	v_pk_add_f32 v[88:89], v[52:53], v[216:217]
	v_pk_add_f32 v[50:51], v[50:51], v[214:215]
	v_cvt_pk_bf16_f32 v52, v62, v63
	v_cvt_pk_bf16_f32 v53, v64, v65
	v_cvt_pk_bf16_f32 v54, v58, v59
	v_cvt_pk_bf16_f32 v55, v60, v61
	v_cvt_pk_bf16_f32 v56, v56, v57
	v_cvt_pk_bf16_f32 v57, v86, v87
	s_nop 0
	v_cvt_pk_bf16_f32 v58, v50, v51
	v_cvt_pk_bf16_f32 v59, v88, v89
	v_and_b32_e32 v51, 0xffff0000, v52
	v_and_b32_e32 v61, 0xffff0000, v53
	v_and_b32_e32 v63, 0xffff0000, v54
	v_and_b32_e32 v65, 0xffff0000, v55
	v_and_b32_e32 v87, 0xffff0000, v56
	v_and_b32_e32 v89, 0xffff0000, v57
	v_and_b32_e32 v91, 0xffff0000, v58
	v_and_b32_e32 v93, 0xffff0000, v59
	v_lshlrev_b32_e32 v50, 16, v52
	v_lshlrev_b32_e32 v60, 16, v53
	v_lshlrev_b32_e32 v62, 16, v54
	v_lshlrev_b32_e32 v64, 16, v55
	v_lshlrev_b32_e32 v86, 16, v56
	v_lshlrev_b32_e32 v88, 16, v57
	v_lshlrev_b32_e32 v90, 16, v58
	v_lshlrev_b32_e32 v92, 16, v59
	v_mul_f32_e32 v51, v51, v51
	v_mul_f32_e32 v61, v61, v61
	v_mul_f32_e32 v63, v63, v63
	v_mul_f32_e32 v65, v65, v65
	v_mul_f32_e32 v87, v87, v87
	v_mul_f32_e32 v89, v89, v89
	v_mul_f32_e32 v91, v91, v91
	v_mul_f32_e32 v93, v93, v93
	v_fmac_f32_e32 v51, v50, v50
	v_fmac_f32_e32 v61, v60, v60
	v_fmac_f32_e32 v63, v62, v62
	v_fmac_f32_e32 v65, v64, v64
	v_fmac_f32_e32 v87, v86, v86
	v_fmac_f32_e32 v89, v88, v88
	v_fmac_f32_e32 v91, v90, v90
	v_fmac_f32_e32 v93, v92, v92
	v_add_f32_e32 v50, v51, v61
	v_add_f32_e32 v51, v63, v65
	v_add_f32_e32 v60, v87, v89
	v_add_f32_e32 v61, v91, v93
	v_add_f32_e32 v50, v50, v51
	v_add_f32_e32 v51, v60, v61
	v_add_f32_e32 v50, v50, v51
	ds_bpermute_b32 v51, v122, v50
	v_lshlrev_b64 v[60:61], 11, v[84:85]
	v_lshl_add_u64 v[60:61], s[2:3], 0, v[60:61]
	v_lshl_add_u64 v[60:61], v[148:149], 1, v[60:61]
	s_waitcnt vmcnt(4)
	global_store_dwordx4 v[60:61], v[52:55], off
	global_store_dwordx4 v[60:61], v[56:59], off offset:256
	s_waitcnt lgkmcnt(0)
	v_add_f32_e32 v50, v50, v51
	ds_bpermute_b32 v51, v123, v50
	s_and_saveexec_b64 s[4:5], vcc
	s_cbranch_execz .LBB0_630
	v_lshlrev_b64 v[52:53], 6, v[84:85]
	v_lshl_add_u64 v[52:53], s[8:9], 0, v[52:53]
	s_lshl_b32 s12, s34, 2
	v_lshl_add_u64 v[52:53], v[52:53], 0, s[12:13]
	s_waitcnt lgkmcnt(0)
	v_add_f32_e32 v50, v50, v51
	global_store_dword v[52:53], v50, off

.LBB0_632:
	s_or_b64 exec, exec, s[4:5]
	v_readlane_b32 s80, v242, 21
	v_readlane_b32 s81, v242, 22
	v_add_u32_e32 v52, 0xa0, v150
	v_readlane_b32 s82, v242, 23
	v_readlane_b32 s83, v242, 24
	s_mov_b64 s[36:37], s[80:81]
	v_add_u32_e32 v34, 0xffffc0a0, v150
	v_ashrrev_i32_e32 v53, 31, v52
	v_cmp_gt_i32_e64 s[4:5], s45, v52
	s_mov_b64 s[38:39], s[82:83]
	v_mov_b32_e32 v38, s39
	s_waitcnt lgkmcnt(0)
	v_cndmask_b32_e64 v35, 0, v53, s[4:5]
	v_cndmask_b32_e64 v34, v34, v52, s[4:5]
	v_mov_b32_e32 v39, s37
	v_mov_b32_e32 v40, s38
	v_mov_b32_e32 v41, s36
	v_cndmask_b32_e64 v37, v38, v39, s[4:5]
	v_cndmask_b32_e64 v36, v40, v41, s[4:5]
	v_lshlrev_b64 v[34:35], 12, v[34:35]
	v_lshl_add_u64 v[34:35], v[36:37], 0, v[34:35]
	v_lshl_add_u64 v[34:35], v[34:35], 0, v[152:153]
	v_add_u32_e32 v50, 0xb0, v150
	v_add_u32_e32 v34, 0xffffc0b0, v150
	v_ashrrev_i32_e32 v51, 31, v50
	v_cmp_gt_i32_e64 s[4:5], s45, v50
	v_readlane_b32 s84, v242, 25
	v_readlane_b32 s85, v242, 26
	v_cndmask_b32_e64 v35, 0, v51, s[4:5]
	v_cndmask_b32_e64 v34, v34, v50, s[4:5]
	v_cndmask_b32_e64 v37, v38, v39, s[4:5]
	v_cndmask_b32_e64 v36, v40, v41, s[4:5]
	v_lshlrev_b64 v[34:35], 12, v[34:35]
	v_lshl_add_u64 v[34:35], v[36:37], 0, v[34:35]
	v_lshl_add_u64 v[38:39], v[34:35], 0, v[152:153]
	global_load_dwordx4 v[42:45], v[38:39], off offset:16
	global_load_dwordx4 v[46:49], v[38:39], off
	global_load_dwordx4 v[34:37], v[38:39], off offset:528
	s_nop 0
	global_load_dwordx4 v[38:41], v[38:39], off offset:512
	v_readlane_b32 s86, v242, 27
	v_readlane_b32 s87, v242, 28
	v_readlane_b32 s88, v242, 29
	v_readlane_b32 s89, v242, 30
	v_readlane_b32 s90, v242, 31
	v_readlane_b32 s91, v242, 32
	v_readlane_b32 s92, v242, 33
	v_readlane_b32 s93, v242, 34
	v_readlane_b32 s94, v242, 35
	v_readlane_b32 s95, v242, 36
	s_waitcnt vmcnt(8)
	v_pk_add_f32 v[32:33], v[32:33], v[188:189]
	v_pk_add_f32 v[30:31], v[30:31], v[186:187]
	v_pk_add_f32 v[28:29], v[28:29], v[192:193]
	v_pk_add_f32 v[26:27], v[26:27], v[190:191]
	v_pk_add_f32 v[54:55], v[24:25], v[196:197]
	v_pk_add_f32 v[24:25], v[22:23], v[194:195]
	v_pk_add_f32 v[56:57], v[20:21], v[200:201]
	v_pk_add_f32 v[18:19], v[18:19], v[198:199]
	v_cvt_pk_bf16_f32 v20, v30, v31
	v_cvt_pk_bf16_f32 v21, v32, v33
	v_cvt_pk_bf16_f32 v22, v26, v27
	v_cvt_pk_bf16_f32 v23, v28, v29
	v_cvt_pk_bf16_f32 v24, v24, v25
	v_cvt_pk_bf16_f32 v25, v54, v55
	s_nop 0
	v_cvt_pk_bf16_f32 v26, v18, v19
	v_cvt_pk_bf16_f32 v27, v56, v57
	v_and_b32_e32 v19, 0xffff0000, v20
	v_and_b32_e32 v29, 0xffff0000, v21
	v_and_b32_e32 v31, 0xffff0000, v22
	v_and_b32_e32 v33, 0xffff0000, v23
	v_and_b32_e32 v55, 0xffff0000, v24
	v_and_b32_e32 v57, 0xffff0000, v25
	v_and_b32_e32 v59, 0xffff0000, v26
	v_and_b32_e32 v61, 0xffff0000, v27
	v_lshlrev_b32_e32 v18, 16, v20
	v_lshlrev_b32_e32 v28, 16, v21
	v_lshlrev_b32_e32 v30, 16, v22
	v_lshlrev_b32_e32 v32, 16, v23
	v_lshlrev_b32_e32 v54, 16, v24
	v_lshlrev_b32_e32 v56, 16, v25
	v_lshlrev_b32_e32 v58, 16, v26
	v_lshlrev_b32_e32 v60, 16, v27
	v_mul_f32_e32 v19, v19, v19
	v_mul_f32_e32 v29, v29, v29
	v_mul_f32_e32 v31, v31, v31
	v_mul_f32_e32 v33, v33, v33
	v_mul_f32_e32 v55, v55, v55
	v_mul_f32_e32 v57, v57, v57
	v_mul_f32_e32 v59, v59, v59
	v_mul_f32_e32 v61, v61, v61
	v_fmac_f32_e32 v19, v18, v18
	v_fmac_f32_e32 v29, v28, v28
	v_fmac_f32_e32 v31, v30, v30
	v_fmac_f32_e32 v33, v32, v32
	v_fmac_f32_e32 v55, v54, v54
	v_fmac_f32_e32 v57, v56, v56
	v_fmac_f32_e32 v59, v58, v58
	v_fmac_f32_e32 v61, v60, v60
	v_add_f32_e32 v18, v19, v29
	v_add_f32_e32 v19, v31, v33
	v_add_f32_e32 v28, v55, v57
	v_add_f32_e32 v29, v59, v61
	v_add_f32_e32 v18, v18, v19
	v_add_f32_e32 v19, v28, v29
	v_add_f32_e32 v18, v18, v19
	ds_bpermute_b32 v19, v122, v18
	v_lshlrev_b64 v[28:29], 11, v[52:53]
	v_lshl_add_u64 v[28:29], s[2:3], 0, v[28:29]
	v_lshl_add_u64 v[28:29], v[148:149], 1, v[28:29]
	s_waitcnt vmcnt(0)
	global_store_dwordx4 v[28:29], v[20:23], off
	global_store_dwordx4 v[28:29], v[24:27], off offset:256
	s_waitcnt lgkmcnt(0)
	v_add_f32_e32 v18, v18, v19
	ds_bpermute_b32 v19, v123, v18
	s_and_saveexec_b64 s[4:5], vcc
	s_cbranch_execz .LBB0_634
	v_lshlrev_b64 v[20:21], 6, v[52:53]
	v_lshl_add_u64 v[20:21], s[8:9], 0, v[20:21]
	s_lshl_b32 s12, s34, 2
	v_lshl_add_u64 v[20:21], v[20:21], 0, s[12:13]
	s_waitcnt lgkmcnt(0)
	v_add_f32_e32 v18, v18, v19
	global_store_dword v[20:21], v18, off
